# mLSTM unit prologue: five conv tap/bias loads issued together (bit-identical)
# baseline (speedup 1.0000x reference)
; #define conv_w KIN(5)
; #define conv_b KIN(6)
; __device__ __forceinline__ void mlstm_unit(int unit, int l, const bf16_t* proj, const float* gif, const float* conv_w, const float* conv_b, bf16_t* mpart, float* dpart, int gplanes, LAS unsigned char* lds) {
;     ...
;     if (tid < 64) nvec[tid] = 0.f;
;     if (tid < 128) {
;         const float* cw = conv_w + (size_t)l * 4 * 2048; const float* cb = conv_b + (size_t)l * 2048;
;         const int gcol = (tid >> 6) * 1024 + h * 256 + dq * 64 + (tid & 63);
; #pragma unroll
;         for (int tap = 0; tap < 4; ++tap) CWL[tap * 128 + tid] = cw[tap * 2048 + gcol];
;         CWL[4 * 128 + tid] = cb[gcol];
;     }
.LBB0_400:
	s_or_b64 exec, exec, s[38:39]
	v_cmp_gt_i32_e64 s[38:39], 64, v112
	v_lshl_add_u32 v2, v112, 2, 0
	s_and_saveexec_b64 s[46:47], s[38:39]
	v_add_u32_e32 v3, 0x21400, v2
	ds_write_b32 v3, v0
	s_or_b64 exec, exec, s[46:47]
	s_movk_i32 s7, 0x7f
	s_bfe_u32 s4, s83, 0x20002
	s_and_b32 s6, s83, 3
	v_cmp_lt_i32_e32 vcc, s7, v112
	s_and_saveexec_b64 s[46:47], vcc
	s_xor_b64 s[46:47], exec, s[46:47]
	s_lshl_b32 s7, s4, 8
	s_lshl_b32 s36, s6, 6
	s_or_saveexec_b64 s[46:47], s[46:47]
	v_and_b32_e32 v44, 63, v112
	v_mov_b32_e32 v3, s36
	v_mov_b32_e32 v24, s7
	s_xor_b64 exec, exec, s[46:47]
	s_cbranch_execz .LBB0_406
	s_waitcnt lgkmcnt(0)
	s_add_u32 s48, s48, s84
	s_addc_u32 s49, s49, s85
	s_lshl_b32 s7, s4, 8
	v_lshl_or_b32 v1, v1, 10, s7
	s_lshl_b32 s8, s6, 6
	v_or3_b32 v4, v1, s8, v44
	v_ashrrev_i32_e32 v5, 31, v4
	v_add_u32_e32 v1, 0x20400, v2
	v_lshlrev_b64 v[2:3], 2, v[4:5]
	v_lshl_add_u64 v[4:5], s[48:49], 0, v[2:3]
	s_movk_i32 s6, 0x2000
	v_add_co_u32_e32 v6, vcc, s6, v4
	global_load_dword v8, v[4:5], off
	s_nop 0
	v_addc_co_u32_e32 v7, vcc, 0, v5, vcc
	global_load_dword v9, v[6:7], off
	s_movk_i32 s6, 0x4000
	v_mov_b32_e32 v24, s7
	v_add_co_u32_e32 v10, vcc, s6, v4
	s_add_u32 s6, s44, s34
	s_nop 0
	v_addc_co_u32_e32 v11, vcc, 0, v5, vcc
	v_add_co_u32_e32 v12, vcc, 0x6000, v4
	s_addc_u32 s7, s45, s35
	s_nop 0
	v_addc_co_u32_e32 v13, vcc, 0, v5, vcc
	v_lshl_add_u64 v[2:3], s[6:7], 0, v[2:3]
	global_load_dword v14, v[10:11], off
	global_load_dword v15, v[12:13], off
	global_load_dword v16, v[2:3], off
	v_mov_b32_e32 v3, s8
	s_waitcnt vmcnt(0)
	ds_write2st64_b32 v1, v8, v9 offset1:2
	ds_write2st64_b32 v1, v14, v15 offset0:4 offset1:6
	ds_write_b32 v1, v16 offset:2048
